# P1: explicit store drain (s_waitcnt vmcnt(0)) at each unit start, before the next K-loop issues its first stage loads; on top of v52
# speedup vs baseline: 1.0099x; 1.0020x over previous
; template <class Epi, class Sched, bool ALIGN_EPI = false, bool SP2 = false>
; __device__ __forceinline__ void gemm_phase(PG8_LAS unsigned char* lds, const Gemm g, const Sched& S, const Epi& E, int wid_in) {
;     ...
;         const bool has_next = S.next(ui + 1, nxt);
;         const char* nA = has_next ? (const char*)g.A + (size_t)nxt.pm * tstep : cA; const char* nB = has_next ? (const char*)g.Bt + (size_t)nxt.pn * tstep : cB;
;         for (int t = 0; t < nt; t += 2) {
;             const bool last = (t == nt - 2);
;             if constexpr (Epi::HAS_MID) { if (t == nt / 2) E.mid(acc, cur, wr, wc, fr, fq); }
;             const char* a1 = cA + (size_t)(t + 1) * kstep;
;             const char* a2 = last ? nA : cA + (size_t)(t + 2) * kstep; const char* b2 = last ? nB : cB + (size_t)(t + 2) * kstep;
;             const char* a3 = a2 + kstep; const char* b3 = b2 + kstep;
;     ...
; #pragma unroll
;         for (int a = 0; a < 2; ++a)
; #pragma unroll
;             for (int b = 0; b < 2; ++b)
; #pragma unroll
;                 for (int m = 0; m < 4; ++m)
; #pragma unroll
;                     for (int n = 0; n < 2; ++n) acc[a][b][m][n] = (f32x4){0.f, 0.f, 0.f, 0.f};
.LBB0_226:
	s_waitcnt vmcnt(0)
	s_ashr_i32 s83, s82, 31
	s_lshl_b64 s[84:85], s[82:83], 19
	s_add_u32 s84, s8, s84
	s_addc_u32 s85, s9, s85
	s_and_b64 s[86:87], s[0:1], exec
	s_cselect_b32 s3, s85, s69
	s_cselect_b32 s5, s84, s68
	s_ashr_i32 s81, s80, 31
	s_lshl_b64 s[86:87], s[80:81], 19
	s_add_u32 s86, s13, s86
	s_addc_u32 s87, s33, s87
	s_and_b64 s[90:91], s[0:1], exec
	s_cselect_b32 s81, s87, s89
	s_cselect_b32 s83, s86, s88
	s_add_u32 s68, s68, 0x40080
	s_addc_u32 s69, s69, 0
	s_add_u32 s92, s88, 0x100
	v_mov_b32_e32 v0, 0
	s_addc_u32 s93, s89, 0
	s_mov_b32 s94, -2
	v_mov_b32_e32 v1, v0
	v_mov_b32_e32 v2, v0
	v_mov_b32_e32 v3, v0
	v_mov_b32_e32 v4, v0
	v_mov_b32_e32 v5, v0
	v_mov_b32_e32 v6, v0
	v_mov_b32_e32 v7, v0
	v_mov_b32_e32 v16, v0
	v_mov_b32_e32 v17, v0
	v_mov_b32_e32 v18, v0
	v_mov_b32_e32 v19, v0
	v_mov_b32_e32 v20, v0
	v_mov_b32_e32 v21, v0
	v_mov_b32_e32 v22, v0
	v_mov_b32_e32 v23, v0
	v_mov_b32_e32 v32, v0
	v_mov_b32_e32 v33, v0
	v_mov_b32_e32 v34, v0
	v_mov_b32_e32 v35, v0
	v_mov_b32_e32 v36, v0
	v_mov_b32_e32 v37, v0
	v_mov_b32_e32 v38, v0
	v_mov_b32_e32 v39, v0
	v_mov_b32_e32 v48, v0
	v_mov_b32_e32 v49, v0
	v_mov_b32_e32 v50, v0
	v_mov_b32_e32 v51, v0
	v_mov_b32_e32 v52, v0
	v_mov_b32_e32 v53, v0
	v_mov_b32_e32 v54, v0
	v_mov_b32_e32 v55, v0
	v_mov_b32_e32 v8, v0
	v_mov_b32_e32 v9, v0
	v_mov_b32_e32 v10, v0
	v_mov_b32_e32 v11, v0
	v_mov_b32_e32 v12, v0
	v_mov_b32_e32 v13, v0
	v_mov_b32_e32 v14, v0
	v_mov_b32_e32 v15, v0
	v_mov_b32_e32 v24, v0
	v_mov_b32_e32 v25, v0
	v_mov_b32_e32 v26, v0
	v_mov_b32_e32 v27, v0
	v_mov_b32_e32 v28, v0
	v_mov_b32_e32 v29, v0
	v_mov_b32_e32 v30, v0
	v_mov_b32_e32 v31, v0
	v_mov_b32_e32 v40, v0
	v_mov_b32_e32 v41, v0
	v_mov_b32_e32 v42, v0
	v_mov_b32_e32 v43, v0
	v_mov_b32_e32 v44, v0
	v_mov_b32_e32 v45, v0
	v_mov_b32_e32 v46, v0
	v_mov_b32_e32 v47, v0
	v_mov_b32_e32 v56, v0
	v_mov_b32_e32 v57, v0
	v_mov_b32_e32 v58, v0
	v_mov_b32_e32 v59, v0
	v_mov_b32_e32 v60, v0
	v_mov_b32_e32 v61, v0
	v_mov_b32_e32 v62, v0
	v_mov_b32_e32 v63, v0
	v_mov_b32_e32 v64, v0
	v_mov_b32_e32 v65, v0
	v_mov_b32_e32 v66, v0
	v_mov_b32_e32 v67, v0
	v_mov_b32_e32 v68, v0
	v_mov_b32_e32 v69, v0
	v_mov_b32_e32 v70, v0
	v_mov_b32_e32 v71, v0
	v_mov_b32_e32 v80, v0
	v_mov_b32_e32 v81, v0
	v_mov_b32_e32 v82, v0
	v_mov_b32_e32 v83, v0
	v_mov_b32_e32 v84, v0
	v_mov_b32_e32 v85, v0
	v_mov_b32_e32 v86, v0
	v_mov_b32_e32 v87, v0
	v_mov_b32_e32 v96, v0
	v_mov_b32_e32 v97, v0
	v_mov_b32_e32 v98, v0
	v_mov_b32_e32 v99, v0
	v_mov_b32_e32 v100, v0
	v_mov_b32_e32 v101, v0
	v_mov_b32_e32 v102, v0
	v_mov_b32_e32 v103, v0
	v_mov_b32_e32 v112, v0
	v_mov_b32_e32 v113, v0
	v_mov_b32_e32 v114, v0
	v_mov_b32_e32 v115, v0
	v_mov_b32_e32 v116, v0
	v_mov_b32_e32 v117, v0
	v_mov_b32_e32 v118, v0
	v_mov_b32_e32 v119, v0
	v_mov_b32_e32 v72, v0
	v_mov_b32_e32 v73, v0
	v_mov_b32_e32 v74, v0
	v_mov_b32_e32 v75, v0
	v_mov_b32_e32 v76, v0
	v_mov_b32_e32 v77, v0
	v_mov_b32_e32 v78, v0
	v_mov_b32_e32 v79, v0
	v_mov_b32_e32 v88, v0
	v_mov_b32_e32 v89, v0
	v_mov_b32_e32 v90, v0
	v_mov_b32_e32 v91, v0
	v_mov_b32_e32 v92, v0
	v_mov_b32_e32 v93, v0
	v_mov_b32_e32 v94, v0
	v_mov_b32_e32 v95, v0
	v_mov_b32_e32 v104, v0
	v_mov_b32_e32 v105, v0
	v_mov_b32_e32 v106, v0
	v_mov_b32_e32 v107, v0
	v_mov_b32_e32 v108, v0
	v_mov_b32_e32 v109, v0
	v_mov_b32_e32 v110, v0
	v_mov_b32_e32 v111, v0
	v_mov_b32_e32 v120, v0
	v_mov_b32_e32 v121, v0
	v_mov_b32_e32 v122, v0
	v_mov_b32_e32 v123, v0
	v_mov_b32_e32 v124, v0
	v_mov_b32_e32 v125, v0
	v_mov_b32_e32 v126, v0
	v_mov_b32_e32 v127, v0
	.p2align	6
